# P0 RMSNorm rows: gain vectors preloaded once per wave (no per-row serialized gain loads)
# baseline (speedup 1.0000x reference)
.LBB0_28:
	s_add_u32 s56, s92, 0x2400000
	s_addc_u32 s57, s93, 0
	s_cmpk_gt_i32 s0, 0x201f
	v_mbcnt_lo_u32_b32 v169, -1, 0
	s_cbranch_scc1 .LBB0_33
	v_mbcnt_hi_u32_b32 v1, -1, v169
	v_and_b32_e32 v3, 64, v1
	v_add_u32_e32 v3, 64, v3
	v_xor_b32_e32 v4, 1, v1
	v_cmp_lt_i32_e32 vcc, v4, v3
	v_mov_b32_e32 v33, 0
	v_lshlrev_b32_e32 v32, 4, v0
	v_cndmask_b32_e32 v4, v1, v4, vcc
	v_lshlrev_b32_e32 v47, 2, v4
	v_xor_b32_e32 v4, 2, v1
	v_cmp_lt_i32_e32 vcc, v4, v3
	v_lshl_add_u64 v[34:35], s[54:55], 0, v[32:33]
	s_mov_b64 s[4:5], 0x1000
	v_cndmask_b32_e32 v4, v1, v4, vcc
	v_lshlrev_b32_e32 v48, 2, v4
	v_xor_b32_e32 v4, 4, v1
	v_cmp_lt_i32_e32 vcc, v4, v3
	v_lshl_add_u64 v[38:39], v[34:35], 0, s[4:5]
	s_mov_b64 s[4:5], 0x1400
	v_cndmask_b32_e32 v4, v1, v4, vcc
	v_lshlrev_b32_e32 v49, 2, v4
	v_xor_b32_e32 v4, 8, v1
	v_cmp_lt_i32_e32 vcc, v4, v3
	v_lshl_add_u64 v[40:41], v[34:35], 0, s[4:5]
	s_mov_b64 s[4:5], 0x1800
	v_cndmask_b32_e32 v4, v1, v4, vcc
	v_lshlrev_b32_e32 v50, 2, v4
	v_xor_b32_e32 v4, 16, v1
	v_cmp_lt_i32_e32 vcc, v4, v3
	v_lshl_add_u64 v[42:43], v[34:35], 0, s[4:5]
	s_mov_b64 s[4:5], 0x1c00
	v_cndmask_b32_e32 v4, v1, v4, vcc
	v_lshlrev_b32_e32 v51, 2, v4
	v_xor_b32_e32 v4, 32, v1
	s_ashr_i32 s1, s0, 31
	v_cmp_lt_i32_e32 vcc, v4, v3
	v_lshl_add_u64 v[44:45], v[34:35], 0, s[4:5]
	s_ashr_i32 s71, s70, 31
	s_lshl_b64 s[4:5], s[0:1], 13
	v_cndmask_b32_e32 v1, v1, v4, vcc
	v_mov_b32_e32 v3, v33
	s_add_u32 s8, s44, s4
	s_mov_b32 s7, 0
	v_lshlrev_b32_e32 v52, 2, v1
	v_lshl_add_u64 v[36:37], s[56:57], 0, v[2:3]
	s_addc_u32 s9, s45, s5
	s_lshl_b64 s[10:11], s[70:71], 13
	v_lshlrev_b32_e32 v32, 4, v0
	s_movk_i32 s15, 0x1000
	v_mov_b32_e32 v53, 0x358637bd
	s_mov_b32 s16, 0xf800000
	v_mov_b32_e32 v54, 0x260
	global_load_dwordx4 v[200:203], v[34:35], off
	global_load_dwordx4 v[204:207], v[34:35], off offset:1024
	global_load_dwordx4 v[208:211], v[34:35], off offset:2048
	global_load_dwordx4 v[212:215], v[34:35], off offset:3072
	global_load_dwordx4 v[216:219], v[38:39], off
	global_load_dwordx4 v[220:223], v[40:41], off
	global_load_dwordx4 v[224:227], v[42:43], off
	global_load_dwordx4 v[228:231], v[44:45], off
	s_branch .LBB0_31
.LBB0_30:
	global_load_dwordx4 v[24:27], v32, s[12:13] nt
	global_load_dwordx4 v[4:7], v32, s[12:13] offset:1024 nt
	global_load_dwordx4 v[20:23], v32, s[12:13] offset:2048 nt
	global_load_dwordx4 v[8:11], v32, s[12:13] offset:3072 nt
	v_lshl_add_u64 v[0:1], s[12:13], 0, v[32:33]
	v_add_co_u32_e32 v16, vcc, s15, v0
	s_lshl_b64 s[12:13], s[4:5], 12
	s_nop 0
	v_addc_co_u32_e32 v17, vcc, 0, v1, vcc
	global_load_dwordx4 v[12:15], v[16:17], off offset:1024 nt
	global_load_dwordx4 v[28:31], v[16:17], off nt
	global_load_dwordx4 v[0:3], v[16:17], off offset:3072 nt
	s_nop 0
	global_load_dwordx4 v[16:19], v[16:17], off offset:2048 nt
	s_nop 0
	s_add_u32 s0, s0, s70
	s_addc_u32 s1, s1, s71
	s_add_u32 s8, s8, s10
	s_addc_u32 s9, s9, s11
	s_cmpk_gt_i32 s0, 0x201f
	s_waitcnt vmcnt(7)
	v_mov_b32_e32 v62, v25
	s_waitcnt vmcnt(6)
	v_mov_b32_e32 v63, v5
	v_mov_b32_e32 v66, v27
	v_mov_b32_e32 v67, v7
	v_mov_b32_e32 v60, v24
	v_mov_b32_e32 v61, v4
	v_mov_b32_e32 v64, v26
	v_mov_b32_e32 v65, v6
	s_waitcnt vmcnt(5)
	v_pk_mul_f32 v[68:69], v[22:23], v[22:23]
	v_pk_mul_f32 v[70:71], v[20:21], v[20:21]
	v_pk_mul_f32 v[62:63], v[62:63], v[62:63]
	v_pk_mul_f32 v[66:67], v[66:67], v[66:67]
	v_pk_mov_b32 v[76:77], v[70:71], v[68:69] op_sel:[1,0]
	v_mov_b32_e32 v71, v69
	v_pk_fma_f32 v[60:61], v[60:61], v[60:61], v[62:63]
	v_pk_fma_f32 v[62:63], v[64:65], v[64:65], v[66:67]
	s_waitcnt vmcnt(4)
	v_mul_f32_e32 v72, v9, v9
	v_mul_f32_e32 v74, v11, v11
	v_pk_add_f32 v[64:65], v[76:77], v[70:71]
	v_pk_add_f32 v[60:61], v[60:61], v[62:63]
	v_pk_fma_f32 v[68:69], v[8:9], v[8:9], v[72:73] op_sel_hi:[1,1,0]
	v_pk_fma_f32 v[72:73], v[10:11], v[10:11], v[74:75] op_sel_hi:[1,1,0]
	s_waitcnt vmcnt(2)
	v_mul_f32_e32 v55, v28, v28
	v_mul_f32_e32 v77, v29, v29
	v_pk_add_f32 v[64:65], v[64:65], v[64:65] op_sel:[0,1] op_sel_hi:[1,0]
	v_pk_add_f32 v[60:61], v[60:61], v[60:61] op_sel:[0,1] op_sel_hi:[1,0]
	v_pk_mul_f32 v[66:67], v[14:15], v[14:15]
	v_pk_mul_f32 v[70:71], v[12:13], v[12:13]
	v_mul_f32_e32 v69, v30, v30
	v_mul_f32_e32 v73, v31, v31
	v_mov_b32_e32 v65, v77
	v_mov_b32_e32 v61, v55
	v_pk_mov_b32 v[62:63], v[70:71], v[66:67] op_sel:[1,0]
	v_mov_b32_e32 v71, v67
	v_pk_add_f32 v[68:69], v[68:69], v[72:73]
	v_pk_add_f32 v[60:61], v[60:61], v[64:65]
	s_waitcnt vmcnt(0)
	v_mul_f32_e32 v74, v17, v17
	v_mul_f32_e32 v76, v19, v19
	v_pk_add_f32 v[62:63], v[62:63], v[70:71]
	v_pk_add_f32 v[60:61], v[60:61], v[68:69]
	v_mul_f32_e32 v78, v2, v2
	v_mul_f32_e32 v79, v3, v3
	v_mul_f32_e32 v80, v0, v0
	v_mul_f32_e32 v81, v1, v1
	v_pk_fma_f32 v[66:67], v[16:17], v[16:17], v[74:75] op_sel_hi:[1,1,0]
	v_pk_fma_f32 v[74:75], v[18:19], v[18:19], v[76:77] op_sel_hi:[1,1,0]
	v_pk_add_f32 v[62:63], v[62:63], v[62:63] op_sel:[0,1] op_sel_hi:[1,0]
	v_pk_add_f32 v[60:61], v[60:61], v[60:61] op_sel:[0,1] op_sel_hi:[1,0]
	v_mov_b32_e32 v67, v78
	v_mov_b32_e32 v75, v79
	v_mov_b32_e32 v63, v81
	v_mov_b32_e32 v61, v80
	v_pk_add_f32 v[66:67], v[66:67], v[74:75]
	v_pk_add_f32 v[60:61], v[60:61], v[62:63]
	s_nop 0
	v_pk_add_f32 v[60:61], v[60:61], v[66:67]
	s_nop 0
	v_add_f32_e32 v55, v60, v61
	ds_bpermute_b32 v60, v47, v55
	s_waitcnt lgkmcnt(0)
	v_add_f32_e32 v55, v55, v60
	ds_bpermute_b32 v60, v48, v55
	s_waitcnt lgkmcnt(0)
	v_add_f32_e32 v55, v55, v60
	ds_bpermute_b32 v60, v49, v55
	s_waitcnt lgkmcnt(0)
	v_add_f32_e32 v55, v55, v60
	ds_bpermute_b32 v60, v50, v55
	s_waitcnt lgkmcnt(0)
	v_add_f32_e32 v55, v55, v60
	ds_bpermute_b32 v60, v51, v55
	s_waitcnt lgkmcnt(0)
	v_add_f32_e32 v55, v55, v60
	ds_bpermute_b32 v60, v52, v55
	s_waitcnt lgkmcnt(0)
	v_add_f32_e32 v55, v55, v60
	v_fmamk_f32 v55, v55, 0x3a000000, v53
	v_mul_f32_e32 v60, 0x4f800000, v55
	v_cmp_gt_f32_e32 vcc, s16, v55
	s_nop 1
	v_cndmask_b32_e32 v55, v55, v60, vcc
	v_sqrt_f32_e32 v60, v55
	s_nop 0
	v_add_u32_e32 v61, -1, v60
	v_add_u32_e32 v62, 1, v60
	v_fma_f32 v63, -v61, v60, v55
	v_fma_f32 v64, -v62, v60, v55
	v_cmp_ge_f32_e64 s[4:5], 0, v63
	s_nop 1
	v_cndmask_b32_e64 v60, v60, v61, s[4:5]
	v_cmp_lt_f32_e64 s[4:5], 0, v64
	s_nop 1
	v_cndmask_b32_e64 v60, v60, v62, s[4:5]
	v_mul_f32_e32 v61, 0x37800000, v60
	v_cndmask_b32_e32 v60, v60, v61, vcc
	v_cmp_class_f32_e32 vcc, v55, v54
	s_nop 1
	v_cndmask_b32_e32 v55, v60, v55, vcc
	v_div_scale_f32 v62, s[4:5], v55, v55, 1.0
	v_rcp_f32_e32 v63, v62
	v_div_scale_f32 v64, vcc, 1.0, v55, 1.0
	v_lshl_add_u64 v[60:61], v[36:37], 0, s[12:13]
	v_fma_f32 v65, -v62, v63, 1.0
	v_fmac_f32_e32 v63, v65, v63
	v_mul_f32_e32 v65, v64, v63
	v_fma_f32 v66, -v62, v65, v64
	v_fmac_f32_e32 v65, v66, v63
	v_fma_f32 v62, -v62, v65, v64
	v_div_fmas_f32 v62, v62, v63, v65
	v_div_fixup_f32 v62, v62, v55, 1.0
	v_pk_mul_f32 v[24:25], v[24:25], v[62:63] op_sel_hi:[1,0]
	v_pk_mul_f32 v[26:27], v[26:27], v[62:63] op_sel_hi:[1,0]
	v_pk_mul_f32 v[24:25], v[200:201], v[24:25]
	v_pk_mul_f32 v[26:27], v[202:203], v[26:27]
	v_cvt_pk_bf16_f32 v24, v24, v25
	v_cvt_pk_bf16_f32 v25, v26, v27
	global_store_dwordx2 v[60:61], v[24:25], off
	s_nop 0
	v_pk_mul_f32 v[4:5], v[4:5], v[62:63] op_sel_hi:[1,0]
	v_pk_mul_f32 v[6:7], v[6:7], v[62:63] op_sel_hi:[1,0]
	v_pk_mul_f32 v[20:21], v[20:21], v[62:63] op_sel_hi:[1,0]
	v_pk_mul_f32 v[22:23], v[22:23], v[62:63] op_sel_hi:[1,0]
	v_pk_mul_f32 v[8:9], v[8:9], v[62:63] op_sel_hi:[1,0]
	v_pk_mul_f32 v[10:11], v[10:11], v[62:63] op_sel_hi:[1,0]
	v_pk_mul_f32 v[0:1], v[0:1], v[62:63] op_sel_hi:[1,0]
	v_pk_mul_f32 v[2:3], v[2:3], v[62:63] op_sel_hi:[1,0]
	v_pk_mul_f32 v[4:5], v[204:205], v[4:5]
	v_pk_mul_f32 v[6:7], v[206:207], v[6:7]
	v_cvt_pk_bf16_f32 v4, v4, v5
	v_cvt_pk_bf16_f32 v5, v6, v7
	global_store_dwordx2 v[60:61], v[4:5], off offset:512
	s_nop 0
	v_pk_mul_f32 v[4:5], v[208:209], v[20:21]
	v_pk_mul_f32 v[6:7], v[210:211], v[22:23]
	v_cvt_pk_bf16_f32 v4, v4, v5
	v_cvt_pk_bf16_f32 v5, v6, v7
	global_store_dwordx2 v[60:61], v[4:5], off offset:1024
	s_nop 0
	v_pk_mul_f32 v[4:5], v[8:9], v[212:213]
	v_pk_mul_f32 v[6:7], v[10:11], v[214:215]
	v_cvt_pk_bf16_f32 v4, v4, v5
	v_cvt_pk_bf16_f32 v5, v6, v7
	global_store_dwordx2 v[60:61], v[4:5], off offset:1536
	s_nop 0
	v_pk_mul_f32 v[8:9], v[28:29], v[62:63] op_sel_hi:[1,0]
	v_pk_mul_f32 v[10:11], v[30:31], v[62:63] op_sel_hi:[1,0]
	v_pk_mul_f32 v[4:5], v[8:9], v[216:217]
	v_pk_mul_f32 v[6:7], v[10:11], v[218:219]
	v_cvt_pk_bf16_f32 v4, v4, v5
	v_cvt_pk_bf16_f32 v5, v6, v7
	global_store_dwordx2 v[60:61], v[4:5], off offset:2048
	s_nop 0
	v_pk_mul_f32 v[8:9], v[12:13], v[62:63] op_sel_hi:[1,0]
	v_pk_mul_f32 v[10:11], v[14:15], v[62:63] op_sel_hi:[1,0]
	v_pk_mul_f32 v[4:5], v[8:9], v[220:221]
	v_pk_mul_f32 v[6:7], v[10:11], v[222:223]
	v_cvt_pk_bf16_f32 v4, v4, v5
	v_cvt_pk_bf16_f32 v5, v6, v7
	global_store_dwordx2 v[60:61], v[4:5], off offset:2560
	s_nop 0
	v_pk_mul_f32 v[8:9], v[16:17], v[62:63] op_sel_hi:[1,0]
	v_pk_mul_f32 v[10:11], v[18:19], v[62:63] op_sel_hi:[1,0]
	v_pk_mul_f32 v[4:5], v[8:9], v[224:225]
	v_pk_mul_f32 v[6:7], v[10:11], v[226:227]
	v_cvt_pk_bf16_f32 v4, v4, v5
	v_cvt_pk_bf16_f32 v5, v6, v7
	global_store_dwordx2 v[60:61], v[4:5], off offset:3072
	s_nop 0
	v_pk_mul_f32 v[0:1], v[0:1], v[228:229]
	v_pk_mul_f32 v[2:3], v[2:3], v[230:231]
	v_cvt_pk_bf16_f32 v0, v0, v1
	v_cvt_pk_bf16_f32 v1, v2, v3
	global_store_dwordx2 v[60:61], v[0:1], off offset:3584
	s_nop 0
	s_cbranch_scc1 .LBB0_33
